# main GEMM unit header drains all but the last four epilogue stores (their data lives in registers the k-loop never writes)
# speedup vs baseline: 1.0034x; 1.0034x over previous
.LBB0_371:
	s_add_u32 s6, s20, 0x80080
	s_addc_u32 s7, s21, 0
	s_add_u32 s13, s10, 0x100
	v_mov_b32_e32 v0, 0
	s_addc_u32 s15, s11, 0
	s_mov_b32 s20, -2
	v_mov_b32_e32 v1, v0
	s_waitcnt lgkmcnt(0)
	v_mov_b32_e32 v2, v0
	v_mov_b32_e32 v3, v0
	v_mov_b32_e32 v4, v0
	v_mov_b32_e32 v5, v0
	v_mov_b32_e32 v6, v0
	v_mov_b32_e32 v7, v0
	v_mov_b32_e32 v16, v0
	v_mov_b32_e32 v17, v0
	v_mov_b32_e32 v18, v0
	v_mov_b32_e32 v19, v0
	v_mov_b32_e32 v20, v0
	v_mov_b32_e32 v21, v0
	v_mov_b32_e32 v22, v0
	v_mov_b32_e32 v23, v0
	v_mov_b32_e32 v34, v0
	v_mov_b32_e32 v35, v0
	v_mov_b32_e32 v36, v0
	v_mov_b32_e32 v37, v0
	v_mov_b32_e32 v38, v0
	v_mov_b32_e32 v39, v0
	v_mov_b32_e32 v40, v0
	v_mov_b32_e32 v41, v0
	v_mov_b32_e32 v50, v0
	v_mov_b32_e32 v51, v0
	v_mov_b32_e32 v52, v0
	v_mov_b32_e32 v53, v0
	v_mov_b32_e32 v54, v0
	v_mov_b32_e32 v55, v0
	v_mov_b32_e32 v56, v0
	v_mov_b32_e32 v57, v0
	v_mov_b32_e32 v8, v0
	v_mov_b32_e32 v9, v0
	v_mov_b32_e32 v10, v0
	v_mov_b32_e32 v11, v0
	v_mov_b32_e32 v12, v0
	v_mov_b32_e32 v13, v0
	v_mov_b32_e32 v14, v0
	v_mov_b32_e32 v15, v0
	v_mov_b32_e32 v24, v0
	v_mov_b32_e32 v25, v0
	v_mov_b32_e32 v26, v0
	v_mov_b32_e32 v27, v0
	v_mov_b32_e32 v28, v0
	v_mov_b32_e32 v29, v0
	v_mov_b32_e32 v30, v0
	v_mov_b32_e32 v31, v0
	v_mov_b32_e32 v42, v0
	v_mov_b32_e32 v43, v0
	v_mov_b32_e32 v44, v0
	v_mov_b32_e32 v45, v0
	v_mov_b32_e32 v46, v0
	v_mov_b32_e32 v47, v0
	v_mov_b32_e32 v48, v0
	v_mov_b32_e32 v49, v0
	v_mov_b32_e32 v58, v0
	v_mov_b32_e32 v59, v0
	v_mov_b32_e32 v60, v0
	v_mov_b32_e32 v61, v0
	v_mov_b32_e32 v62, v0
	v_mov_b32_e32 v63, v0
	v_mov_b32_e32 v64, v0
	v_mov_b32_e32 v65, v0
	v_mov_b32_e32 v66, v0
	v_mov_b32_e32 v67, v0
	v_mov_b32_e32 v68, v0
	v_mov_b32_e32 v69, v0
	v_mov_b32_e32 v70, v0
	v_mov_b32_e32 v71, v0
	v_mov_b32_e32 v72, v0
	v_mov_b32_e32 v73, v0
	v_mov_b32_e32 v82, v0
	v_mov_b32_e32 v83, v0
	v_mov_b32_e32 v84, v0
	v_mov_b32_e32 v85, v0
	v_mov_b32_e32 v86, v0
	v_mov_b32_e32 v87, v0
	v_mov_b32_e32 v88, v0
	v_mov_b32_e32 v89, v0
	v_mov_b32_e32 v98, v0
	v_mov_b32_e32 v99, v0
	v_mov_b32_e32 v100, v0
	v_mov_b32_e32 v101, v0
	v_mov_b32_e32 v102, v0
	v_mov_b32_e32 v103, v0
	v_mov_b32_e32 v104, v0
	v_mov_b32_e32 v105, v0
	v_mov_b32_e32 v114, v0
	v_mov_b32_e32 v115, v0
	v_mov_b32_e32 v116, v0
	v_mov_b32_e32 v117, v0
	v_mov_b32_e32 v118, v0
	v_mov_b32_e32 v119, v0
	v_mov_b32_e32 v120, v0
	v_mov_b32_e32 v121, v0
	v_mov_b32_e32 v74, v0
	v_mov_b32_e32 v75, v0
	v_mov_b32_e32 v76, v0
	v_mov_b32_e32 v77, v0
	v_mov_b32_e32 v78, v0
	v_mov_b32_e32 v79, v0
	v_mov_b32_e32 v80, v0
	v_mov_b32_e32 v81, v0
	v_mov_b32_e32 v90, v0
	v_mov_b32_e32 v91, v0
	v_mov_b32_e32 v92, v0
	v_mov_b32_e32 v93, v0
	v_mov_b32_e32 v94, v0
	v_mov_b32_e32 v95, v0
	v_mov_b32_e32 v96, v0
	v_mov_b32_e32 v97, v0
	v_mov_b32_e32 v106, v0
	v_mov_b32_e32 v107, v0
	v_mov_b32_e32 v108, v0
	v_mov_b32_e32 v109, v0
	v_mov_b32_e32 v110, v0
	v_mov_b32_e32 v111, v0
	v_mov_b32_e32 v112, v0
	v_mov_b32_e32 v113, v0
	v_mov_b32_e32 v122, v0
	v_mov_b32_e32 v123, v0
	v_mov_b32_e32 v124, v0
	v_mov_b32_e32 v125, v0
	v_mov_b32_e32 v126, v0
	v_mov_b32_e32 v127, v0
	v_mov_b32_e32 v128, v0
	v_mov_b32_e32 v129, v0
	s_waitcnt vmcnt(4)
